# attention phase: one static s_setprio 1 for the younger wave half (waves 4-7) across the A/B unit loops, reset to 0 after; on top of full-line epilogues + permlane ssq
# baseline (speedup 1.0000x reference)
.LBB0_249:
.LBB0_250:
	v_readfirstlane_b32 s93, v168
	s_nop 3
	s_bitcmp1_b32 s93, 8
	s_cbranch_scc0 .Lprio_done
	s_setprio 1

.LBB0_297:
	s_setprio 0
	s_waitcnt vmcnt(0) lgkmcnt(0)
	s_barrier
